# static s_setprio 1 for the younger wave half (waves 4-7) in the attention work-queue loop (asm guide 7.4), replacing 20 B of pad, on top of v13
# baseline (speedup 1.0000x reference)
; #define PH(n) if (!((SKIPMASK >> (n)) & 1))
; __global__ void __launch_bounds__(512, 2) fwd_kernel(Args a) {
;     ...
;     PH(14) { unsigned* actr = (unsigned*)(ws + WS_BAR) + 3584;
;         unsigned u = (unsigned)gw;
;         while (u < 1056u * 8u) {
;             unsigned nx = 0; if (lane == 0) nx = atomicAdd(actr, 1u) + (unsigned)NGW;
;             if (u < 256u) { const int uu = (int)(8192u + u); attn_unit<false>(a, QB, AO, KB, VT, uu >> 3, uu & 7, lane); } else { const int uu = (int)(u - 256u); attn_unit<true>(a, QB, AO, KB, VT, uu >> 3, uu & 7, lane); }
;             u = (unsigned)__builtin_amdgcn_readfirstlane((int)nx); } }
.LBB0_593:
	v_readlane_b32 s98, v241, 22
	s_cmp_lt_u32 s98, 4
	s_cbranch_scc1 .Latt_oldhalf
	s_setprio 1
